# P5 z-tile staging by direct HBM->LDS loads (global_load_lds_dwordx4, one tile row per wave instruction, 16 in flight) instead of VGPR staging + ds_write
# speedup vs baseline: 1.0054x; 1.0045x over previous
; #define LAS __attribute__((address_space(3)))
; __device__ __forceinline__ f32x16 mfma32(bf16x8 a, bf16x8 b, f32x16 c) { return __builtin_amdgcn_mfma_f32_32x32x16_bf16(a, b, c, 0, 0, 0); }
; __device__ __forceinline__ void phase_ssd_y(const PT& p, LAS unsigned char* lds, int tid, int lane, int wave) {
;     ...
;         for (int i = 0; i < 16; ++i) { const int pid = tid + 512 * i, row = pid >> 6, c8 = pid & 63;
;             *(LAS u32x4*)(tile + row * SY_TP + 16 * c8) = *(const u32x4*)(Ycat + ((size_t)tok0 + row) * 4096 + 2048 + grp * 512 + 8 * c8); }
;     ...
;         for (int st = 0; st < 8; ++st) cf[st] = ld_frag16(Cn + tok * 512 + grp * 128 + 16 * st + 8 * h);
;         f32x16 X[4];
; #pragma unroll
;         for (int sb = 0; sb < 4; ++sb) {
; #pragma unroll
;             for (int i = 0; i < 16; ++i) X[sb][i] = 0.f;
;             if (sb <= lb) {
; #pragma unroll
;                 for (int st = 0; st < 8; ++st) X[sb] = mfma32(ld_frag16(Bn + ((size_t)tok0 + sb * 32 + r32) * 512 + grp * 128 + 16 * st + 8 * h), cf[st], X[sb]);
;             }
.LBB0_485:
	v_readfirstlane_b32 s98, v117
	s_lshl_b32 s99, s1, 1
	s_lshr_b32 s98, s98, 6
	s_add_u32 s100, s98, s92
	s_addc_u32 s101, s93, 0
	s_lshl_b64 s[100:101], s[100:101], 13
	s_add_u32 s100, s100, s88
	s_addc_u32 s101, s101, s89
	s_add_u32 s100, s100, s99
	s_addc_u32 s101, s101, 0
	s_add_u32 s100, s100, 0x1000
	s_addc_u32 s101, s101, 0
	s_mul_i32 s98, s98, 0x410
	s_add_i32 s98, s98, 0x2600
	s_mov_b32 m0, s98
	s_add_i32 s98, s98, 0x2080
	global_load_lds_dwordx4 v120, s[100:101]
	s_add_u32 s100, s100, 0x10000
	s_addc_u32 s101, s101, 0
	s_mov_b32 m0, s98
	s_add_i32 s98, s98, 0x2080
	global_load_lds_dwordx4 v120, s[100:101]
	s_add_u32 s100, s100, 0x10000
	s_addc_u32 s101, s101, 0
	s_mov_b32 m0, s98
	s_add_i32 s98, s98, 0x2080
	global_load_lds_dwordx4 v120, s[100:101]
	s_add_u32 s100, s100, 0x10000
	s_addc_u32 s101, s101, 0
	s_mov_b32 m0, s98
	s_add_i32 s98, s98, 0x2080
	global_load_lds_dwordx4 v120, s[100:101]
	s_add_u32 s100, s100, 0x10000
	s_addc_u32 s101, s101, 0
	s_mov_b32 m0, s98
	s_add_i32 s98, s98, 0x2080
	global_load_lds_dwordx4 v120, s[100:101]
	s_add_u32 s100, s100, 0x10000
	s_addc_u32 s101, s101, 0
	s_mov_b32 m0, s98
	s_add_i32 s98, s98, 0x2080
	global_load_lds_dwordx4 v120, s[100:101]
	s_add_u32 s100, s100, 0x10000
	s_addc_u32 s101, s101, 0
	s_mov_b32 m0, s98
	s_add_i32 s98, s98, 0x2080
	global_load_lds_dwordx4 v120, s[100:101]
	s_add_u32 s100, s100, 0x10000
	s_addc_u32 s101, s101, 0
	s_mov_b32 m0, s98
	s_add_i32 s98, s98, 0x2080
	global_load_lds_dwordx4 v120, s[100:101]
	s_add_u32 s100, s100, 0x10000
	s_addc_u32 s101, s101, 0
	s_mov_b32 m0, s98
	s_add_i32 s98, s98, 0x2080
	global_load_lds_dwordx4 v120, s[100:101]
	s_add_u32 s100, s100, 0x10000
	s_addc_u32 s101, s101, 0
	s_mov_b32 m0, s98
	s_add_i32 s98, s98, 0x2080
	global_load_lds_dwordx4 v120, s[100:101]
	s_add_u32 s100, s100, 0x10000
	s_addc_u32 s101, s101, 0
	s_mov_b32 m0, s98
	s_add_i32 s98, s98, 0x2080
	global_load_lds_dwordx4 v120, s[100:101]
	s_add_u32 s100, s100, 0x10000
	s_addc_u32 s101, s101, 0
	s_mov_b32 m0, s98
	s_add_i32 s98, s98, 0x2080
	global_load_lds_dwordx4 v120, s[100:101]
	s_add_u32 s100, s100, 0x10000
	s_addc_u32 s101, s101, 0
	s_mov_b32 m0, s98
	s_add_i32 s98, s98, 0x2080
	global_load_lds_dwordx4 v120, s[100:101]
	s_add_u32 s100, s100, 0x10000
	s_addc_u32 s101, s101, 0
	s_mov_b32 m0, s98
	s_add_i32 s98, s98, 0x2080
	global_load_lds_dwordx4 v120, s[100:101]
	s_add_u32 s100, s100, 0x10000
	s_addc_u32 s101, s101, 0
	s_mov_b32 m0, s98
	s_add_i32 s98, s98, 0x2080
	global_load_lds_dwordx4 v120, s[100:101]
	s_add_u32 s100, s100, 0x10000
	s_addc_u32 s101, s101, 0
	s_mov_b32 m0, s98
	s_add_i32 s98, s98, 0x2080
	global_load_lds_dwordx4 v120, s[100:101]
	s_add_u32 s100, s100, 0x10000
	s_addc_u32 s101, s101, 0
	s_waitcnt vmcnt(0)
	v_mov_b32_e32 v1, s93
	v_or_b32_e32 v0, s92, v124
	v_readlane_b32 s80, v249, 16
	v_lshlrev_b64 v[0:1], 10, v[0:1]
	v_readlane_b32 s81, v249, 17
	s_lshl_b32 s96, s3, 8
	v_mov_b32_e32 v141, v121
	v_lshl_add_u64 v[0:1], s[80:81], 0, v[0:1]
	v_lshl_add_u64 v[0:1], v[0:1], 0, s[96:97]
	v_lshl_add_u64 v[0:1], v[0:1], 0, v[140:141]
	s_waitcnt lgkmcnt(0)
	s_barrier
	global_load_dwordx4 v[80:83], v[0:1], off
	global_load_dwordx4 v[84:87], v[0:1], off offset:32
	global_load_dwordx4 v[88:91], v[0:1], off offset:64
	global_load_dwordx4 v[92:95], v[0:1], off offset:96
	global_load_dwordx4 v[96:99], v[0:1], off offset:128
	global_load_dwordx4 v[100:103], v[0:1], off offset:160
	global_load_dwordx4 v[104:107], v[0:1], off offset:192
	global_load_dwordx4 v[108:111], v[0:1], off offset:224
	v_mov_b32_e32 v1, s93
	v_or_b32_e32 v0, s92, v116
	v_lshl_add_u64 v[64:65], v[128:129], 0, s[96:97]
	v_lshlrev_b64 v[0:1], 10, v[0:1]
	v_lshl_add_u64 v[20:21], v[64:65], 0, v[0:1]
	global_load_dwordx4 v[0:3], v[20:21], off
	global_load_dwordx4 v[212:215], v[20:21], off offset:32
	global_load_dwordx4 v[216:219], v[20:21], off offset:64
	global_load_dwordx4 v[220:223], v[20:21], off offset:96
	global_load_dwordx4 v[224:227], v[20:21], off offset:128
	global_load_dwordx4 v[228:231], v[20:21], off offset:160
	global_load_dwordx4 v[232:235], v[20:21], off offset:192
	global_load_dwordx4 v[236:239], v[20:21], off offset:224
	s_and_b64 vcc, exec, s[90:91]
	s_waitcnt vmcnt(7)
	v_mfma_f32_32x32x16_bf16 v[0:15], v[0:3], v[80:83], 0
	s_waitcnt vmcnt(6)
	v_mfma_f32_32x32x16_bf16 v[0:15], v[212:215], v[84:87], v[0:15]
	s_waitcnt vmcnt(5)
	v_mfma_f32_32x32x16_bf16 v[0:15], v[216:219], v[88:91], v[0:15]
	s_waitcnt vmcnt(4)
	v_mfma_f32_32x32x16_bf16 v[0:15], v[220:223], v[92:95], v[0:15]
	s_waitcnt vmcnt(3)
	v_mfma_f32_32x32x16_bf16 v[0:15], v[224:227], v[96:99], v[0:15]
	s_waitcnt vmcnt(2)
	v_mfma_f32_32x32x16_bf16 v[0:15], v[228:231], v[100:103], v[0:15]
	s_waitcnt vmcnt(1)
	v_mfma_f32_32x32x16_bf16 v[0:15], v[232:235], v[104:107], v[0:15]
	s_waitcnt vmcnt(0)
	v_mfma_f32_32x32x16_bf16 v[0:15], v[236:239], v[108:111], v[0:15]
	s_cbranch_vccz .LBB0_488
	v_mov_b32_e32 v17, s93
	v_or_b32_e32 v16, s92, v130
	v_lshlrev_b64 v[16:17], 10, v[16:17]
	v_lshl_add_u64 v[36:37], v[64:65], 0, v[16:17]
	global_load_dwordx4 v[16:19], v[36:37], off
	global_load_dwordx4 v[212:215], v[36:37], off offset:32
	global_load_dwordx4 v[216:219], v[36:37], off offset:64
	global_load_dwordx4 v[220:223], v[36:37], off offset:96
	global_load_dwordx4 v[224:227], v[36:37], off offset:128
	global_load_dwordx4 v[228:231], v[36:37], off offset:160
	global_load_dwordx4 v[232:235], v[36:37], off offset:192
	global_load_dwordx4 v[236:239], v[36:37], off offset:224
	s_waitcnt vmcnt(7)
	v_mfma_f32_32x32x16_bf16 v[16:31], v[16:19], v[80:83], 0
	s_waitcnt vmcnt(6)
	v_mfma_f32_32x32x16_bf16 v[16:31], v[212:215], v[84:87], v[16:31]
	s_waitcnt vmcnt(5)
	v_mfma_f32_32x32x16_bf16 v[16:31], v[216:219], v[88:91], v[16:31]
	s_waitcnt vmcnt(4)
	v_mfma_f32_32x32x16_bf16 v[16:31], v[220:223], v[92:95], v[16:31]
	s_waitcnt vmcnt(3)
	v_mfma_f32_32x32x16_bf16 v[16:31], v[224:227], v[96:99], v[16:31]
	s_waitcnt vmcnt(2)
	v_mfma_f32_32x32x16_bf16 v[16:31], v[228:231], v[100:103], v[16:31]
	s_waitcnt vmcnt(1)
	v_mfma_f32_32x32x16_bf16 v[16:31], v[232:235], v[104:107], v[16:31]
	s_waitcnt vmcnt(0)
	v_mfma_f32_32x32x16_bf16 v[16:31], v[236:239], v[108:111], v[16:31]
	s_branch .LBB0_489
